# v80 plus pooling MFMA stage: fragment reads issued one 4-read block ahead (rolling buffers) instead of right before each MFMA pair
# baseline (speedup 1.0000x reference)
; #define LAS __attribute__((address_space(3)))
; __device__ __forceinline__ unsigned pk2(float lo, float hi) { return pg8::cvt_pk_bf16(lo, hi); }
; template <int WIN>
; __device__ __forceinline__ void pool_block_t(LAS unsigned char* lds, const Ptrs& P, int g, int tile0, int tstep, int tid) {
;     ...
;         for (int rep = 0; rep < 2; ++rep) {
;             const int row = vrow0 + 32 * rep; const int pos = (tile * 64 + row) & 2047; const int cnt = (pos + 1 < WIN) ? pos + 1 : WIN;
;             const v4u cur = *(const LAS v4u*)(Us + (row + 15) * S136 + vseg * 8); float a[8];
; #pragma unroll
;             for (int k = 0; k < 4; ++k) { a[2 * k] = bflo(cur[k]); a[2 * k + 1] = bfhi(cur[k]); }
; #pragma unroll
;             for (int tau = 1; tau < WIN; ++tau) { const v4u v = *(const LAS v4u*)(Us + (row + 15 - tau) * S136 + vseg * 8);
; #pragma unroll
;                 for (int k = 0; k < 4; ++k) { a[2 * k] += bflo(v[k]); a[2 * k + 1] += bfhi(v[k]); } }
;             const float inv = __builtin_amdgcn_rcpf((float)cnt); v4u o;
; #pragma unroll
;             for (int k = 0; k < 4; ++k) o[k] = pk2(a[2 * k] * inv - bflo(cur[k]), a[2 * k + 1] * inv - bfhi(cur[k]));
;             *(LAS v4u*)(Ps + row * S136 + vseg * 8) = o;
.LBB0_538:
	s_and_b32 s58, s72, 0x7c0
	v_or_b32_e32 v28, s58, v80
	v_min_u32_e32 v124, 15, v28
	ds_read_b128 v[64:67], v185 offset:4080
	ds_read_b128 v[52:55], v185 offset:3808
	ds_read_b128 v[28:31], v185 offset:2448
	ds_read_b128 v[32:35], v185 offset:2176
	ds_read_b128 v[68:71], v185 offset:3536
	ds_read_b128 v[56:59], v185 offset:3264
	ds_read_b128 v[44:47], v185 offset:2992
	ds_read_b128 v[40:43], v185 offset:2720
	s_waitcnt lgkmcnt(7)
	v_lshlrev_b32_e32 v208, 16, v64
	v_and_b32_e32 v209, 0xffff0000, v64
	s_waitcnt lgkmcnt(6)
	v_lshlrev_b32_e32 v210, 16, v52
	v_and_b32_e32 v211, 0xffff0000, v52
	s_waitcnt lgkmcnt(3)
	v_lshlrev_b32_e32 v212, 16, v68
	v_and_b32_e32 v213, 0xffff0000, v68
	v_pk_add_f32 v[210:211], v[208:209], v[210:211]
	ds_read_b128 v[36:39], v185 offset:1904
	s_waitcnt lgkmcnt(3)
	v_lshlrev_b32_e32 v214, 16, v56
	v_and_b32_e32 v215, 0xffff0000, v56
	v_pk_add_f32 v[210:211], v[210:211], v[212:213]
	v_lshlrev_b32_e32 v134, 16, v32
	v_and_b32_e32 v135, 0xffff0000, v32
	v_lshlrev_b32_e32 v136, 16, v33
	v_and_b32_e32 v137, 0xffff0000, v33
	v_lshlrev_b32_e32 v138, 16, v34
	v_and_b32_e32 v139, 0xffff0000, v34
	v_lshlrev_b32_e32 v126, 16, v35
	v_and_b32_e32 v127, 0xffff0000, v35
	ds_read_b128 v[32:35], v185 offset:1632
	s_waitcnt lgkmcnt(3)
	v_lshlrev_b32_e32 v216, 16, v44
	v_and_b32_e32 v217, 0xffff0000, v44
	v_pk_add_f32 v[210:211], v[210:211], v[214:215]
	s_waitcnt lgkmcnt(2)
	v_lshlrev_b32_e32 v218, 16, v40
	v_and_b32_e32 v219, 0xffff0000, v40
	v_pk_add_f32 v[210:211], v[210:211], v[216:217]
	v_lshlrev_b32_e32 v220, 16, v28
	v_and_b32_e32 v221, 0xffff0000, v28
	v_pk_add_f32 v[210:211], v[210:211], v[218:219]
	s_waitcnt lgkmcnt(1)
	v_lshlrev_b32_e32 v140, 16, v36
	v_pk_add_f32 v[210:211], v[210:211], v[220:221]
	v_and_b32_e32 v141, 0xffff0000, v36
	v_pk_add_f32 v[134:135], v[210:211], v[134:135]
	s_waitcnt lgkmcnt(0)
	v_lshlrev_b32_e32 v202, 16, v32
	v_and_b32_e32 v203, 0xffff0000, v32
	v_pk_add_f32 v[134:135], v[134:135], v[140:141]
	v_lshlrev_b32_e32 v142, 16, v37
	v_and_b32_e32 v143, 0xffff0000, v37
	v_lshlrev_b32_e32 v200, 16, v38
	v_and_b32_e32 v201, 0xffff0000, v38
	v_lshlrev_b32_e32 v128, 16, v39
	v_and_b32_e32 v129, 0xffff0000, v39
	v_lshlrev_b32_e32 v204, 16, v33
	v_and_b32_e32 v205, 0xffff0000, v33
	v_lshlrev_b32_e32 v206, 16, v34
	v_and_b32_e32 v207, 0xffff0000, v34
	v_lshlrev_b32_e32 v130, 16, v35
	v_and_b32_e32 v131, 0xffff0000, v35
	ds_read_b128 v[76:79], v185 offset:1360
	ds_read_b128 v[72:75], v185 offset:1088
	ds_read_b128 v[60:63], v185 offset:816
	ds_read_b128 v[48:51], v185 offset:544
	ds_read_b128 v[36:39], v185 offset:272
	ds_read_b128 v[32:35], v185
	v_pk_add_f32 v[134:135], v[134:135], v[202:203]
	s_waitcnt lgkmcnt(5)
	v_lshlrev_b32_e32 v140, 16, v76
	v_and_b32_e32 v141, 0xffff0000, v76
	v_add_u32_e32 v124, 1, v124
	v_pk_add_f32 v[134:135], v[134:135], v[140:141]
	s_waitcnt lgkmcnt(4)
	v_lshlrev_b32_e32 v140, 16, v72
	v_and_b32_e32 v141, 0xffff0000, v72
	v_cvt_f32_ubyte0_e32 v124, v124
	v_pk_add_f32 v[134:135], v[134:135], v[140:141]
	s_waitcnt lgkmcnt(3)
	v_lshlrev_b32_e32 v140, 16, v60
	v_and_b32_e32 v141, 0xffff0000, v60
	v_rcp_iflag_f32_e32 v124, v124
	v_pk_add_f32 v[134:135], v[134:135], v[140:141]
	s_waitcnt lgkmcnt(2)
	v_lshlrev_b32_e32 v140, 16, v48
	v_and_b32_e32 v141, 0xffff0000, v48
	v_lshlrev_b32_e32 v64, 16, v65
	v_and_b32_e32 v65, 0xffff0000, v65
	v_lshlrev_b32_e32 v52, 16, v53
	v_and_b32_e32 v53, 0xffff0000, v53
	v_pk_add_f32 v[134:135], v[134:135], v[140:141]
	s_waitcnt lgkmcnt(1)
	v_lshlrev_b32_e32 v140, 16, v36
	v_and_b32_e32 v141, 0xffff0000, v36
	v_lshlrev_b32_e32 v68, 16, v69
	v_and_b32_e32 v69, 0xffff0000, v69
	v_pk_add_f32 v[52:53], v[64:65], v[52:53]
	v_pk_add_f32 v[134:135], v[134:135], v[140:141]
	s_waitcnt lgkmcnt(0)
	v_lshlrev_b32_e32 v140, 16, v32
	v_and_b32_e32 v141, 0xffff0000, v32
	v_lshlrev_b32_e32 v56, 16, v57
	v_and_b32_e32 v57, 0xffff0000, v57
	v_pk_add_f32 v[52:53], v[52:53], v[68:69]
	v_pk_add_f32 v[134:135], v[134:135], v[140:141]
	v_lshlrev_b32_e32 v44, 16, v45
	v_and_b32_e32 v45, 0xffff0000, v45
	v_pk_add_f32 v[52:53], v[52:53], v[56:57]
	v_pk_fma_f32 v[134:135], v[124:125], v[134:135], v[208:209] op_sel_hi:[0,1,1] neg_lo:[0,0,1] neg_hi:[0,0,1]
	v_lshlrev_b32_e32 v40, 16, v41
	v_and_b32_e32 v41, 0xffff0000, v41
	v_pk_add_f32 v[44:45], v[52:53], v[44:45]
	v_cvt_pk_bf16_f32 v28, v134, v135
	v_lshlrev_b32_e32 v134, 16, v29
	v_and_b32_e32 v135, 0xffff0000, v29
	v_pk_add_f32 v[40:41], v[44:45], v[40:41]
	v_lshlrev_b32_e32 v44, 16, v77
	v_pk_add_f32 v[40:41], v[40:41], v[134:135]
	v_and_b32_e32 v45, 0xffff0000, v77
	v_pk_add_f32 v[40:41], v[40:41], v[136:137]
	v_lshlrev_b32_e32 v36, 16, v37
	v_pk_add_f32 v[40:41], v[40:41], v[142:143]
	v_and_b32_e32 v37, 0xffff0000, v37
	v_pk_add_f32 v[40:41], v[40:41], v[204:205]
	v_lshlrev_b32_e32 v32, 16, v33
	v_pk_add_f32 v[40:41], v[40:41], v[44:45]
	v_lshlrev_b32_e32 v44, 16, v73
	v_and_b32_e32 v45, 0xffff0000, v73
	v_pk_add_f32 v[40:41], v[40:41], v[44:45]
	v_lshlrev_b32_e32 v44, 16, v61
	v_and_b32_e32 v45, 0xffff0000, v61
	v_pk_add_f32 v[40:41], v[40:41], v[44:45]
	v_lshlrev_b32_e32 v44, 16, v49
	v_and_b32_e32 v45, 0xffff0000, v49
	v_pk_add_f32 v[40:41], v[40:41], v[44:45]
	v_and_b32_e32 v33, 0xffff0000, v33
	v_pk_add_f32 v[36:37], v[40:41], v[36:37]
	v_lshlrev_b32_e32 v40, 16, v70
	v_pk_add_f32 v[32:33], v[36:37], v[32:33]
	v_lshlrev_b32_e32 v36, 16, v54
	v_pk_fma_f32 v[32:33], v[124:125], v[32:33], v[64:65] op_sel_hi:[0,1,1] neg_lo:[0,0,1] neg_hi:[0,0,1]
	v_cvt_pk_bf16_f32 v29, v32, v33
	v_lshlrev_b32_e32 v32, 16, v66
	v_and_b32_e32 v33, 0xffff0000, v66
	v_and_b32_e32 v37, 0xffff0000, v54
	v_and_b32_e32 v41, 0xffff0000, v70
; #define LAS __attribute__((address_space(3)))
; __device__ __forceinline__ unsigned pk2(float lo, float hi) { return pg8::cvt_pk_bf16(lo, hi); }
; template <int WIN>
; __device__ __forceinline__ void pool_block_t(LAS unsigned char* lds, const Ptrs& P, int g, int tile0, int tstep, int tid) {
;     ...
;         for (int rep = 0; rep < 2; ++rep) {
;             const int row = vrow0 + 32 * rep; const int pos = (tile * 64 + row) & 2047; const int cnt = (pos + 1 < WIN) ? pos + 1 : WIN;
;             const v4u cur = *(const LAS v4u*)(Us + (row + 15) * S136 + vseg * 8); float a[8];
; #pragma unroll
;             for (int k = 0; k < 4; ++k) { a[2 * k] = bflo(cur[k]); a[2 * k + 1] = bfhi(cur[k]); }
; #pragma unroll
;             for (int tau = 1; tau < WIN; ++tau) { const v4u v = *(const LAS v4u*)(Us + (row + 15 - tau) * S136 + vseg * 8);
; #pragma unroll
;                 for (int k = 0; k < 4; ++k) { a[2 * k] += bflo(v[k]); a[2 * k + 1] += bfhi(v[k]); } }
;             const float inv = __builtin_amdgcn_rcpf((float)cnt); v4u o;
; #pragma unroll
;             for (int k = 0; k < 4; ++k) o[k] = pk2(a[2 * k] * inv - bflo(cur[k]), a[2 * k + 1] * inv - bfhi(cur[k]));
;             *(LAS v4u*)(Ps + row * S136 + vseg * 8) = o;
	v_pk_add_f32 v[36:37], v[32:33], v[36:37]
	v_lshlrev_b32_e32 v44, 16, v58
	v_and_b32_e32 v45, 0xffff0000, v58
	v_pk_add_f32 v[36:37], v[36:37], v[40:41]
	v_lshlrev_b32_e32 v48, 16, v46
	v_and_b32_e32 v49, 0xffff0000, v46
	v_pk_add_f32 v[36:37], v[36:37], v[44:45]
	v_lshlrev_b32_e32 v52, 16, v42
	v_and_b32_e32 v53, 0xffff0000, v42
	v_pk_add_f32 v[36:37], v[36:37], v[48:49]
	v_lshlrev_b32_e32 v56, 16, v30
	v_and_b32_e32 v57, 0xffff0000, v30
	v_pk_add_f32 v[36:37], v[36:37], v[52:53]
	v_lshlrev_b32_e32 v40, 16, v78
	v_pk_add_f32 v[36:37], v[36:37], v[56:57]
	v_and_b32_e32 v41, 0xffff0000, v78
	v_pk_add_f32 v[36:37], v[36:37], v[138:139]
	v_lshlrev_b32_e32 v44, 16, v59
	v_pk_add_f32 v[36:37], v[36:37], v[200:201]
	v_and_b32_e32 v45, 0xffff0000, v59
	v_pk_add_f32 v[36:37], v[36:37], v[206:207]
	v_lshlrev_b32_e32 v46, 16, v47
	v_pk_add_f32 v[36:37], v[36:37], v[40:41]
	v_lshlrev_b32_e32 v40, 16, v74
	v_and_b32_e32 v41, 0xffff0000, v74
	v_pk_add_f32 v[36:37], v[36:37], v[40:41]
	v_lshlrev_b32_e32 v40, 16, v62
	v_and_b32_e32 v41, 0xffff0000, v62
	v_pk_add_f32 v[36:37], v[36:37], v[40:41]
	v_lshlrev_b32_e32 v40, 16, v50
	v_and_b32_e32 v41, 0xffff0000, v50
	v_pk_add_f32 v[36:37], v[36:37], v[40:41]
	v_lshlrev_b32_e32 v40, 16, v38
	v_and_b32_e32 v41, 0xffff0000, v38
	v_pk_add_f32 v[36:37], v[36:37], v[40:41]
	v_lshlrev_b32_e32 v40, 16, v34
	v_and_b32_e32 v41, 0xffff0000, v34
	v_pk_add_f32 v[36:37], v[36:37], v[40:41]
	v_lshlrev_b32_e32 v40, 16, v71
	v_pk_fma_f32 v[32:33], v[124:125], v[36:37], v[32:33] op_sel_hi:[0,1,1] neg_lo:[0,0,1] neg_hi:[0,0,1]
	v_cvt_pk_bf16_f32 v30, v32, v33
	v_lshlrev_b32_e32 v32, 16, v67
	v_and_b32_e32 v33, 0xffff0000, v67
	v_lshlrev_b32_e32 v36, 16, v55
	v_and_b32_e32 v37, 0xffff0000, v55
	v_and_b32_e32 v41, 0xffff0000, v71
	v_pk_add_f32 v[36:37], v[32:33], v[36:37]
	v_and_b32_e32 v47, 0xffff0000, v47
	v_pk_add_f32 v[36:37], v[36:37], v[40:41]
	v_lshlrev_b32_e32 v42, 16, v43
	v_pk_add_f32 v[36:37], v[36:37], v[44:45]
	v_and_b32_e32 v43, 0xffff0000, v43
	v_pk_add_f32 v[36:37], v[36:37], v[46:47]
	v_lshlrev_b32_e32 v48, 16, v31
	v_and_b32_e32 v49, 0xffff0000, v31
	v_pk_add_f32 v[36:37], v[36:37], v[42:43]
	v_lshlrev_b32_e32 v40, 16, v79
	v_pk_add_f32 v[36:37], v[36:37], v[48:49]
	v_and_b32_e32 v41, 0xffff0000, v79
	v_pk_add_f32 v[36:37], v[36:37], v[126:127]
	v_lshlrev_b32_e32 v38, 16, v39
	v_pk_add_f32 v[36:37], v[36:37], v[128:129]
	v_and_b32_e32 v39, 0xffff0000, v39
	v_pk_add_f32 v[36:37], v[36:37], v[130:131]
	v_lshlrev_b32_e32 v34, 16, v35
	v_pk_add_f32 v[36:37], v[36:37], v[40:41]
	v_lshlrev_b32_e32 v40, 16, v75
	v_and_b32_e32 v41, 0xffff0000, v75
	v_pk_add_f32 v[36:37], v[36:37], v[40:41]
	v_lshlrev_b32_e32 v40, 16, v63
	v_and_b32_e32 v41, 0xffff0000, v63
	v_pk_add_f32 v[36:37], v[36:37], v[40:41]
	v_lshlrev_b32_e32 v40, 16, v51
	v_and_b32_e32 v41, 0xffff0000, v51
	v_pk_add_f32 v[36:37], v[36:37], v[40:41]
	v_and_b32_e32 v35, 0xffff0000, v35
	v_pk_add_f32 v[36:37], v[36:37], v[38:39]
	v_add_u32_e32 v79, v184, v187
	v_pk_add_f32 v[34:35], v[36:37], v[34:35]
	s_nop 0
	v_pk_fma_f32 v[32:33], v[124:125], v[34:35], v[32:33] op_sel_hi:[0,1,1] neg_lo:[0,0,1] neg_hi:[0,0,1]
	v_cvt_pk_bf16_f32 v31, v32, v33
	ds_write_b128 v185, v[28:31] offset:21504
	v_add_u32_e32 v28, s72, v186
	v_and_b32_e32 v28, 0x7ff, v28
	v_min_u32_e32 v78, 15, v28
	ds_read_b128 v[52:55], v185 offset:12512
	ds_read_b128 v[40:43], v185 offset:12240
	ds_read_b128 v[48:51], v185 offset:10880
	ds_read_b128 v[44:47], v185 offset:11968
	ds_read_b128 v[36:39], v185 offset:11696
	ds_read_b128 v[32:35], v185 offset:11424
	ds_read_b128 v[28:31], v185 offset:11152
	ds_read_b128 v[56:59], v185 offset:10608
	s_waitcnt lgkmcnt(5)
	v_lshlrev_b32_e32 v134, 16, v48
	v_and_b32_e32 v135, 0xffff0000, v48
	v_lshlrev_b32_e32 v136, 16, v49
	v_and_b32_e32 v137, 0xffff0000, v49
	v_lshlrev_b32_e32 v138, 16, v50
	v_and_b32_e32 v139, 0xffff0000, v50
	v_lshlrev_b32_e32 v76, 16, v51
	v_and_b32_e32 v77, 0xffff0000, v51
	ds_read_b128 v[48:51], v185 offset:10336
	ds_read_b128 v[64:67], v185 offset:10064
	s_waitcnt lgkmcnt(2)
	v_lshlrev_b32_e32 v140, 16, v56
	v_and_b32_e32 v141, 0xffff0000, v56
	v_lshlrev_b32_e32 v142, 16, v57
	v_and_b32_e32 v143, 0xffff0000, v57
	v_lshlrev_b32_e32 v200, 16, v58
	v_and_b32_e32 v201, 0xffff0000, v58
	v_lshlrev_b32_e32 v124, 16, v59
	v_and_b32_e32 v125, 0xffff0000, v59
	s_waitcnt lgkmcnt(1)
	v_lshlrev_b32_e32 v202, 16, v48
	v_and_b32_e32 v203, 0xffff0000, v48
	v_lshlrev_b32_e32 v204, 16, v49
	v_and_b32_e32 v205, 0xffff0000, v49
	v_lshlrev_b32_e32 v206, 16, v50
	v_and_b32_e32 v207, 0xffff0000, v50
	v_lshlrev_b32_e32 v126, 16, v51
	v_and_b32_e32 v127, 0xffff0000, v51
	ds_read_b128 v[72:75], v185 offset:9792
	ds_read_b128 v[68:71], v185 offset:9520
	ds_read_b128 v[60:63], v185 offset:9248
	ds_read_b128 v[56:59], v185 offset:8976
	ds_read_b128 v[128:131], v185 offset:12784
	ds_read_b128 v[48:51], v79
	v_lshlrev_b32_e32 v210, 16, v52
	v_and_b32_e32 v211, 0xffff0000, v52
	v_lshlrev_b32_e32 v212, 16, v40
	s_waitcnt lgkmcnt(1)
; #define LAS __attribute__((address_space(3)))
; #define LBAR() do { asm volatile("s_waitcnt lgkmcnt(0)" ::: "memory"); __builtin_amdgcn_s_barrier(); asm volatile("" ::: "memory"); } while (0)
; __device__ __forceinline__ unsigned pk2(float lo, float hi) { return pg8::cvt_pk_bf16(lo, hi); }
; template <int WIN>
; __device__ __forceinline__ void pool_block_t(LAS unsigned char* lds, const Ptrs& P, int g, int tile0, int tstep, int tid) {
;     ...
;         for (int rep = 0; rep < 2; ++rep) {
;             const int row = vrow0 + 32 * rep; const int pos = (tile * 64 + row) & 2047; const int cnt = (pos + 1 < WIN) ? pos + 1 : WIN;
;             const v4u cur = *(const LAS v4u*)(Us + (row + 15) * S136 + vseg * 8); float a[8];
; #pragma unroll
;             for (int k = 0; k < 4; ++k) { a[2 * k] = bflo(cur[k]); a[2 * k + 1] = bfhi(cur[k]); }
; #pragma unroll
;             for (int tau = 1; tau < WIN; ++tau) { const v4u v = *(const LAS v4u*)(Us + (row + 15 - tau) * S136 + vseg * 8);
; #pragma unroll
;                 for (int k = 0; k < 4; ++k) { a[2 * k] += bflo(v[k]); a[2 * k + 1] += bfhi(v[k]); } }
;             const float inv = __builtin_amdgcn_rcpf((float)cnt); v4u o;
; #pragma unroll
;             for (int k = 0; k < 4; ++k) o[k] = pk2(a[2 * k] * inv - bflo(cur[k]), a[2 * k + 1] * inv - bfhi(cur[k]));
;             *(LAS v4u*)(Ps + row * S136 + vseg * 8) = o;
;         }
;         LBAR();
	v_lshlrev_b32_e32 v208, 16, v128
	v_and_b32_e32 v209, 0xffff0000, v128
	v_and_b32_e32 v213, 0xffff0000, v40
	v_pk_add_f32 v[210:211], v[208:209], v[210:211]
	v_lshlrev_b32_e32 v214, 16, v44
	v_and_b32_e32 v215, 0xffff0000, v44
	v_pk_add_f32 v[210:211], v[210:211], v[212:213]
	v_lshlrev_b32_e32 v216, 16, v36
	v_and_b32_e32 v217, 0xffff0000, v36
	v_pk_add_f32 v[210:211], v[210:211], v[214:215]
	v_lshlrev_b32_e32 v218, 16, v32
	v_and_b32_e32 v219, 0xffff0000, v32
	v_pk_add_f32 v[210:211], v[210:211], v[216:217]
	v_lshlrev_b32_e32 v220, 16, v28
	v_and_b32_e32 v221, 0xffff0000, v28
	v_pk_add_f32 v[210:211], v[210:211], v[218:219]
	v_add_u32_e32 v78, 1, v78
	v_pk_add_f32 v[210:211], v[210:211], v[220:221]
	v_cvt_f32_ubyte0_e32 v78, v78
	v_pk_add_f32 v[134:135], v[210:211], v[134:135]
	v_rcp_iflag_f32_e32 v78, v78
	v_pk_add_f32 v[134:135], v[134:135], v[140:141]
	v_lshlrev_b32_e32 v140, 16, v64
	v_pk_add_f32 v[134:135], v[134:135], v[202:203]
	v_and_b32_e32 v141, 0xffff0000, v64
	v_pk_add_f32 v[134:135], v[134:135], v[140:141]
	v_lshlrev_b32_e32 v140, 16, v72
	v_and_b32_e32 v141, 0xffff0000, v72
	v_pk_add_f32 v[134:135], v[134:135], v[140:141]
	v_lshlrev_b32_e32 v140, 16, v68
	v_and_b32_e32 v141, 0xffff0000, v68
	v_pk_add_f32 v[134:135], v[134:135], v[140:141]
	v_lshlrev_b32_e32 v140, 16, v60
	v_and_b32_e32 v141, 0xffff0000, v60
	v_lshlrev_b32_e32 v128, 16, v129
	v_and_b32_e32 v129, 0xffff0000, v129
	v_lshlrev_b32_e32 v52, 16, v53
	v_and_b32_e32 v53, 0xffff0000, v53
	v_pk_add_f32 v[134:135], v[134:135], v[140:141]
	v_lshlrev_b32_e32 v140, 16, v56
	v_and_b32_e32 v141, 0xffff0000, v56
	v_lshlrev_b32_e32 v40, 16, v41
	v_and_b32_e32 v41, 0xffff0000, v41
	v_pk_add_f32 v[52:53], v[128:129], v[52:53]
	v_pk_add_f32 v[134:135], v[134:135], v[140:141]
	s_waitcnt lgkmcnt(0)
	v_lshlrev_b32_e32 v140, 16, v48
	v_and_b32_e32 v141, 0xffff0000, v48
	v_lshlrev_b32_e32 v44, 16, v45
	v_and_b32_e32 v45, 0xffff0000, v45
	v_pk_add_f32 v[40:41], v[52:53], v[40:41]
	v_pk_add_f32 v[134:135], v[134:135], v[140:141]
	v_lshlrev_b32_e32 v36, 16, v37
	v_and_b32_e32 v37, 0xffff0000, v37
	v_pk_add_f32 v[40:41], v[40:41], v[44:45]
	v_pk_fma_f32 v[134:135], v[78:79], v[134:135], v[208:209] op_sel_hi:[0,1,1] neg_lo:[0,0,1] neg_hi:[0,0,1]
	v_lshlrev_b32_e32 v32, 16, v33
	v_and_b32_e32 v33, 0xffff0000, v33
	v_pk_add_f32 v[36:37], v[40:41], v[36:37]
	v_cvt_pk_bf16_f32 v28, v134, v135
	v_lshlrev_b32_e32 v134, 16, v29
	v_and_b32_e32 v135, 0xffff0000, v29
	v_pk_add_f32 v[32:33], v[36:37], v[32:33]
	v_lshlrev_b32_e32 v36, 16, v65
	v_pk_add_f32 v[32:33], v[32:33], v[134:135]
	v_and_b32_e32 v37, 0xffff0000, v65
	v_pk_add_f32 v[32:33], v[32:33], v[136:137]
	v_lshlrev_b32_e32 v40, 16, v42
	v_pk_add_f32 v[32:33], v[32:33], v[142:143]
	v_and_b32_e32 v41, 0xffff0000, v42
	v_pk_add_f32 v[32:33], v[32:33], v[204:205]
	v_lshlrev_b32_e32 v44, 16, v46
	v_pk_add_f32 v[32:33], v[32:33], v[36:37]
	v_lshlrev_b32_e32 v36, 16, v73
	v_and_b32_e32 v37, 0xffff0000, v73
	v_pk_add_f32 v[32:33], v[32:33], v[36:37]
	v_lshlrev_b32_e32 v36, 16, v69
	v_and_b32_e32 v37, 0xffff0000, v69
	v_pk_add_f32 v[32:33], v[32:33], v[36:37]
	v_lshlrev_b32_e32 v36, 16, v61
	v_and_b32_e32 v37, 0xffff0000, v61
	v_pk_add_f32 v[32:33], v[32:33], v[36:37]
	v_lshlrev_b32_e32 v36, 16, v57
	v_and_b32_e32 v37, 0xffff0000, v57
	v_pk_add_f32 v[32:33], v[32:33], v[36:37]
	v_lshlrev_b32_e32 v36, 16, v49
	v_and_b32_e32 v37, 0xffff0000, v49
	v_pk_add_f32 v[32:33], v[32:33], v[36:37]
	v_lshlrev_b32_e32 v36, 16, v54
	v_pk_fma_f32 v[32:33], v[78:79], v[32:33], v[128:129] op_sel_hi:[0,1,1] neg_lo:[0,0,1] neg_hi:[0,0,1]
	v_cvt_pk_bf16_f32 v29, v32, v33
	v_lshlrev_b32_e32 v32, 16, v130
	v_and_b32_e32 v33, 0xffff0000, v130
	v_and_b32_e32 v37, 0xffff0000, v54
	v_pk_add_f32 v[36:37], v[32:33], v[36:37]
	v_and_b32_e32 v45, 0xffff0000, v46
	v_pk_add_f32 v[36:37], v[36:37], v[40:41]
	v_lshlrev_b32_e32 v48, 16, v38
	v_and_b32_e32 v49, 0xffff0000, v38
	v_pk_add_f32 v[36:37], v[36:37], v[44:45]
	v_lshlrev_b32_e32 v52, 16, v34
	v_and_b32_e32 v53, 0xffff0000, v34
	v_pk_add_f32 v[36:37], v[36:37], v[48:49]
	v_lshlrev_b32_e32 v56, 16, v30
	v_and_b32_e32 v57, 0xffff0000, v30
	v_pk_add_f32 v[36:37], v[36:37], v[52:53]
	v_lshlrev_b32_e32 v40, 16, v66
	v_pk_add_f32 v[36:37], v[36:37], v[56:57]
	v_and_b32_e32 v41, 0xffff0000, v66
	v_pk_add_f32 v[36:37], v[36:37], v[138:139]
	v_lshlrev_b32_e32 v42, 16, v47
	v_pk_add_f32 v[36:37], v[36:37], v[200:201]
	v_lshlrev_b32_e32 v38, 16, v39
	v_pk_add_f32 v[36:37], v[36:37], v[206:207]
	v_and_b32_e32 v39, 0xffff0000, v39
	v_pk_add_f32 v[36:37], v[36:37], v[40:41]
	v_lshlrev_b32_e32 v40, 16, v74
	v_and_b32_e32 v41, 0xffff0000, v74
	v_pk_add_f32 v[36:37], v[36:37], v[40:41]
	v_lshlrev_b32_e32 v40, 16, v70
	v_and_b32_e32 v41, 0xffff0000, v70
	v_pk_add_f32 v[36:37], v[36:37], v[40:41]
	v_lshlrev_b32_e32 v40, 16, v62
	v_and_b32_e32 v41, 0xffff0000, v62
	v_pk_add_f32 v[36:37], v[36:37], v[40:41]
	v_lshlrev_b32_e32 v40, 16, v58
	v_and_b32_e32 v41, 0xffff0000, v58
	v_pk_add_f32 v[36:37], v[36:37], v[40:41]
	v_lshlrev_b32_e32 v40, 16, v50
	v_and_b32_e32 v41, 0xffff0000, v50
	v_pk_add_f32 v[36:37], v[36:37], v[40:41]
	v_lshlrev_b32_e32 v40, 16, v43
	v_pk_fma_f32 v[32:33], v[78:79], v[36:37], v[32:33] op_sel_hi:[0,1,1] neg_lo:[0,0,1] neg_hi:[0,0,1]
	v_cvt_pk_bf16_f32 v30, v32, v33
	v_lshlrev_b32_e32 v32, 16, v131
	v_and_b32_e32 v33, 0xffff0000, v131
	v_lshlrev_b32_e32 v36, 16, v55
	v_and_b32_e32 v37, 0xffff0000, v55
	v_and_b32_e32 v41, 0xffff0000, v43
	v_pk_add_f32 v[36:37], v[32:33], v[36:37]
	v_and_b32_e32 v43, 0xffff0000, v47
	v_pk_add_f32 v[36:37], v[36:37], v[40:41]
	v_lshlrev_b32_e32 v34, 16, v35
	v_pk_add_f32 v[36:37], v[36:37], v[42:43]
	v_and_b32_e32 v35, 0xffff0000, v35
	v_pk_add_f32 v[36:37], v[36:37], v[38:39]
	v_lshlrev_b32_e32 v44, 16, v31
	v_and_b32_e32 v45, 0xffff0000, v31
	v_pk_add_f32 v[34:35], v[36:37], v[34:35]
	v_lshlrev_b32_e32 v36, 16, v67
	v_pk_add_f32 v[34:35], v[34:35], v[44:45]
	v_and_b32_e32 v37, 0xffff0000, v67
	v_pk_add_f32 v[34:35], v[34:35], v[76:77]
	s_mov_b32 s72, s71
	v_pk_add_f32 v[34:35], v[34:35], v[124:125]
	s_nop 0
	v_pk_add_f32 v[34:35], v[34:35], v[126:127]
	s_nop 0
	v_pk_add_f32 v[34:35], v[34:35], v[36:37]
	v_lshlrev_b32_e32 v36, 16, v75
	v_and_b32_e32 v37, 0xffff0000, v75
	v_pk_add_f32 v[34:35], v[34:35], v[36:37]
	v_lshlrev_b32_e32 v36, 16, v71
	v_and_b32_e32 v37, 0xffff0000, v71
	v_pk_add_f32 v[34:35], v[34:35], v[36:37]
	v_lshlrev_b32_e32 v36, 16, v63
	v_and_b32_e32 v37, 0xffff0000, v63
	v_pk_add_f32 v[34:35], v[34:35], v[36:37]
	v_lshlrev_b32_e32 v36, 16, v59
	v_and_b32_e32 v37, 0xffff0000, v59
	v_pk_add_f32 v[34:35], v[34:35], v[36:37]
	v_lshlrev_b32_e32 v36, 16, v51
	v_and_b32_e32 v37, 0xffff0000, v51
	v_pk_add_f32 v[34:35], v[34:35], v[36:37]
	s_nop 0
	v_pk_fma_f32 v[32:33], v[78:79], v[34:35], v[32:33] op_sel_hi:[0,1,1] neg_lo:[0,0,1] neg_hi:[0,0,1]
	v_cvt_pk_bf16_f32 v31, v32, v33
	ds_write_b128 v79, v[28:31] offset:21504
	s_waitcnt lgkmcnt(0)
	s_barrier
; #define LAS __attribute__((address_space(3)))
; #define LBAR() do { asm volatile("s_waitcnt lgkmcnt(0)" ::: "memory"); __builtin_amdgcn_s_barrier(); asm volatile("" ::: "memory"); } while (0)
; __device__ __forceinline__ unsigned pk2(float lo, float hi) { return pg8::cvt_pk_bf16(lo, hi); }
; __device__ __forceinline__ f32x4 mfma16(bf16x8 a, bf16x8 b, f32x4 c) { return __builtin_amdgcn_mfma_f32_16x16x32_bf16(a, b, c, 0, 0, 0); }
; template <int WIN>
; __device__ __forceinline__ void pool_block_t(LAS unsigned char* lds, const Ptrs& P, int g, int tile0, int tstep, int tid) {
;     ...
; #pragma unroll
;         for (int it = 0; it < 4; ++it) { f32x4 acc = (f32x4){0.f, 0.f, 0.f, 0.f};
; #pragma unroll
;             for (int ks = 0; ks < 4; ++ks) { const bf16x8 a = *(const LAS bf16x8*)(Ps + (16 * it + fr) * S136 + 32 * ks + 8 * fq); acc = mfma16(bw[ks], a, acc); }
;             v2u pw; pw.x = pk2(acc[0], acc[1]); pw.y = pk2(acc[2], acc[3]);
;             *(LAS v2u*)(Ys + (16 * it + fr) * S136 + 16 * w + 4 * fq) = pw; }
;         LBAR();
; #pragma unroll
;         for (int rep = 0; rep < 2; ++rep) { const int row = vrow0 + 32 * rep; const size_t t = (size_t)tile * 64 + row;
;             *(v4u*)(P.RS + t * 1024 + 512 + g * 128 + vseg * 8) = *(const LAS v4u*)(Ys + row * S136 + vseg * 8); }
	ds_read_b128 v[224:227], v188 offset:21504
	ds_read_b128 v[228:231], v188 offset:21568
	ds_read_b128 v[232:235], v188 offset:21632
	ds_read_b128 v[236:239], v188 offset:21696
	ds_read_b128 v[240:243], v188 offset:25856
	ds_read_b128 v[244:247], v188 offset:25920
	ds_read_b128 v[252:255], v188 offset:25984
	ds_read_b128 v[32:35], v188 offset:26048
	s_waitcnt lgkmcnt(7)
	v_mfma_f32_16x16x32_bf16 v[28:31], v[0:3], v[224:227], 0
	s_waitcnt lgkmcnt(6)
	v_mfma_f32_16x16x32_bf16 v[28:31], v[4:7], v[228:231], v[28:31]
	s_waitcnt lgkmcnt(5)
	v_mfma_f32_16x16x32_bf16 v[28:31], v[8:11], v[232:235], v[28:31]
	s_waitcnt lgkmcnt(4)
	v_mfma_f32_16x16x32_bf16 v[28:31], v[12:15], v[236:239], v[28:31]
	ds_read_b128 v[224:227], v188 offset:30208
	ds_read_b128 v[228:231], v188 offset:30272
	ds_read_b128 v[232:235], v188 offset:30336
	ds_read_b128 v[236:239], v188 offset:30400
	s_nop 7
	v_cvt_pk_bf16_f32 v28, v28, v29
	v_cvt_pk_bf16_f32 v29, v30, v31
	ds_write_b64 v133, v[28:29] offset:38912
	s_waitcnt lgkmcnt(8)
	v_mfma_f32_16x16x32_bf16 v[28:31], v[0:3], v[240:243], 0
	s_waitcnt lgkmcnt(7)
	v_mfma_f32_16x16x32_bf16 v[28:31], v[4:7], v[244:247], v[28:31]
	s_waitcnt lgkmcnt(6)
	v_mfma_f32_16x16x32_bf16 v[28:31], v[8:11], v[252:255], v[28:31]
	s_waitcnt lgkmcnt(5)
	v_mfma_f32_16x16x32_bf16 v[28:31], v[12:15], v[32:35], v[28:31]
	ds_read_b128 v[240:243], v188 offset:34560
	ds_read_b128 v[244:247], v188 offset:34624
	ds_read_b128 v[252:255], v188 offset:34688
	ds_read_b128 v[32:35], v188 offset:34752
	s_nop 7
	v_cvt_pk_bf16_f32 v28, v28, v29
	v_cvt_pk_bf16_f32 v29, v30, v31
	ds_write_b64 v133, v[28:29] offset:43264
	s_waitcnt lgkmcnt(9)
	v_mfma_f32_16x16x32_bf16 v[28:31], v[0:3], v[224:227], 0
	s_waitcnt lgkmcnt(8)
	v_mfma_f32_16x16x32_bf16 v[28:31], v[4:7], v[228:231], v[28:31]
	s_waitcnt lgkmcnt(7)
	v_mfma_f32_16x16x32_bf16 v[28:31], v[8:11], v[232:235], v[28:31]
	s_waitcnt lgkmcnt(6)
	v_mfma_f32_16x16x32_bf16 v[28:31], v[12:15], v[236:239], v[28:31]
	s_nop 7
	v_cvt_pk_bf16_f32 v28, v28, v29
	v_cvt_pk_bf16_f32 v29, v30, v31
	ds_write_b64 v133, v[28:29] offset:47616
	s_waitcnt lgkmcnt(5)
	v_mfma_f32_16x16x32_bf16 v[28:31], v[0:3], v[240:243], 0
	s_waitcnt lgkmcnt(4)
	v_mfma_f32_16x16x32_bf16 v[28:31], v[4:7], v[244:247], v[28:31]
	s_waitcnt lgkmcnt(3)
	v_mfma_f32_16x16x32_bf16 v[28:31], v[8:11], v[252:255], v[28:31]
	s_waitcnt lgkmcnt(2)
	v_mfma_f32_16x16x32_bf16 v[28:31], v[12:15], v[32:35], v[28:31]
	s_nop 7
	v_cvt_pk_bf16_f32 v28, v28, v29
	v_cvt_pk_bf16_f32 v29, v30, v31
	ds_write_b64 v133, v[28:29] offset:51968
	s_waitcnt lgkmcnt(0)
	s_barrier
	ds_read_b128 v[28:31], v185 offset:38912
	ds_read_b128 v[32:35], v79 offset:38912
	s_waitcnt lgkmcnt(1)
	global_store_dwordx4 v[122:123], v[28:31], off
	s_nop 1
	v_add_co_u32_e32 v28, vcc, 0x10000, v122
	s_nop 1
	v_addc_co_u32_e32 v29, vcc, 0, v123, vcc
	v_lshl_add_u64 v[122:123], v[122:123], 0, s[20:21]
	s_andn2_b64 vcc, exec, s[56:57]
	s_waitcnt lgkmcnt(0)
	global_store_dwordx4 v[28:29], v[32:35], off
	s_cbranch_vccz .LBB0_552
	s_waitcnt vmcnt(2)
	s_branch .Lpool0_top

; #define LAS __attribute__((address_space(3)))
; __device__ __forceinline__ unsigned pk2(float lo, float hi) { return pg8::cvt_pk_bf16(lo, hi); }
; template <int WIN>
; __device__ __forceinline__ void pool_block_t(LAS unsigned char* lds, const Ptrs& P, int g, int tile0, int tstep, int tid) {
;     ...
;         for (int rep = 0; rep < 2; ++rep) {
;             const int row = vrow0 + 32 * rep; const int pos = (tile * 64 + row) & 2047; const int cnt = (pos + 1 < WIN) ? pos + 1 : WIN;
;             const v4u cur = *(const LAS v4u*)(Us + (row + 15) * S136 + vseg * 8); float a[8];
; #pragma unroll
;             for (int k = 0; k < 4; ++k) { a[2 * k] = bflo(cur[k]); a[2 * k + 1] = bfhi(cur[k]); }
; #pragma unroll
;             for (int tau = 1; tau < WIN; ++tau) { const v4u v = *(const LAS v4u*)(Us + (row + 15 - tau) * S136 + vseg * 8);
; #pragma unroll
;                 for (int k = 0; k < 4; ++k) { a[2 * k] += bflo(v[k]); a[2 * k + 1] += bfhi(v[k]); } }
;             const float inv = __builtin_amdgcn_rcpf((float)cnt); v4u o;
; #pragma unroll
;             for (int k = 0; k < 4; ++k) o[k] = pk2(a[2 * k] * inv - bflo(cur[k]), a[2 * k + 1] * inv - bfhi(cur[k]));
;             *(LAS v4u*)(Ps + row * S136 + vseg * 8) = o;
.LBB0_563:
	ds_read_b128 v[34:37], v185 offset:4080
	ds_read_b128 v[38:41], v185 offset:3808
	s_and_b32 s58, s72, 0x7c0
	v_or_b32_e32 v33, s58, v80
	v_min_u32_e32 v33, 7, v33
	s_waitcnt lgkmcnt(1)
	v_lshlrev_b32_e32 v58, 16, v34
	v_and_b32_e32 v59, 0xffff0000, v34
	s_waitcnt lgkmcnt(0)
	v_lshlrev_b32_e32 v66, 16, v38
	v_and_b32_e32 v67, 0xffff0000, v38
	v_lshlrev_b32_e32 v60, 16, v35
	v_and_b32_e32 v61, 0xffff0000, v35
	v_lshlrev_b32_e32 v62, 16, v36
	v_and_b32_e32 v63, 0xffff0000, v36
	v_lshlrev_b32_e32 v64, 16, v37
	v_and_b32_e32 v65, 0xffff0000, v37
	v_lshlrev_b32_e32 v68, 16, v39
	v_and_b32_e32 v69, 0xffff0000, v39
	v_lshlrev_b32_e32 v70, 16, v40
	v_and_b32_e32 v71, 0xffff0000, v40
	v_lshlrev_b32_e32 v72, 16, v41
	v_and_b32_e32 v73, 0xffff0000, v41
	ds_read_b128 v[34:37], v185 offset:3536
	ds_read_b128 v[38:41], v185 offset:3264
	ds_read_b128 v[42:45], v185 offset:2992
	ds_read_b128 v[46:49], v185 offset:2720
	ds_read_b128 v[50:53], v185 offset:2448
	ds_read_b128 v[54:57], v185 offset:2176
	v_pk_add_f32 v[66:67], v[58:59], v[66:67]
	s_waitcnt lgkmcnt(5)
	v_lshlrev_b32_e32 v76, 16, v34
	v_and_b32_e32 v77, 0xffff0000, v34
	v_add_u32_e32 v33, 1, v33
	v_pk_add_f32 v[66:67], v[66:67], v[76:77]
	s_waitcnt lgkmcnt(4)
	v_lshlrev_b32_e32 v76, 16, v38
	v_and_b32_e32 v77, 0xffff0000, v38
	v_cvt_f32_ubyte0_e32 v33, v33
	v_pk_add_f32 v[66:67], v[66:67], v[76:77]
	s_waitcnt lgkmcnt(3)
	v_lshlrev_b32_e32 v76, 16, v42
	v_and_b32_e32 v77, 0xffff0000, v42
	v_rcp_iflag_f32_e32 v74, v33
	v_pk_add_f32 v[66:67], v[66:67], v[76:77]
	s_waitcnt lgkmcnt(2)
	v_lshlrev_b32_e32 v76, 16, v46
	v_and_b32_e32 v77, 0xffff0000, v46
	v_pk_add_f32 v[66:67], v[66:67], v[76:77]
	s_waitcnt lgkmcnt(1)
	v_lshlrev_b32_e32 v76, 16, v50
	v_and_b32_e32 v77, 0xffff0000, v50
	v_pk_add_f32 v[66:67], v[66:67], v[76:77]
	s_waitcnt lgkmcnt(0)
	v_lshlrev_b32_e32 v76, 16, v54
	v_and_b32_e32 v77, 0xffff0000, v54
	v_pk_add_f32 v[66:67], v[66:67], v[76:77]
	v_lshlrev_b32_e32 v38, 16, v39
	v_pk_fma_f32 v[58:59], v[74:75], v[66:67], v[58:59] op_sel_hi:[0,1,1] neg_lo:[0,0,1] neg_hi:[0,0,1]
	v_cvt_pk_bf16_f32 v34, v58, v59
	v_pk_add_f32 v[58:59], v[60:61], v[68:69]
	v_lshlrev_b32_e32 v66, 16, v35
	v_and_b32_e32 v67, 0xffff0000, v35
	v_pk_add_f32 v[58:59], v[58:59], v[66:67]
	v_and_b32_e32 v39, 0xffff0000, v39
	v_pk_add_f32 v[38:39], v[58:59], v[38:39]
	v_lshlrev_b32_e32 v42, 16, v43
	v_and_b32_e32 v43, 0xffff0000, v43
	v_pk_add_f32 v[38:39], v[38:39], v[42:43]
	v_lshlrev_b32_e32 v42, 16, v47
	v_and_b32_e32 v43, 0xffff0000, v47
	v_pk_add_f32 v[38:39], v[38:39], v[42:43]
	v_lshlrev_b32_e32 v42, 16, v51
	v_and_b32_e32 v43, 0xffff0000, v51
	v_pk_add_f32 v[38:39], v[38:39], v[42:43]
	v_lshlrev_b32_e32 v42, 16, v55
	v_and_b32_e32 v43, 0xffff0000, v55
	v_pk_add_f32 v[38:39], v[38:39], v[42:43]
	v_lshlrev_b32_e32 v42, 16, v36
	v_pk_fma_f32 v[38:39], v[74:75], v[38:39], v[60:61] op_sel_hi:[0,1,1] neg_lo:[0,0,1] neg_hi:[0,0,1]
	v_cvt_pk_bf16_f32 v35, v38, v39
	v_pk_add_f32 v[38:39], v[62:63], v[70:71]
	v_and_b32_e32 v43, 0xffff0000, v36
	v_pk_add_f32 v[38:39], v[38:39], v[42:43]
	v_lshlrev_b32_e32 v42, 16, v40
	v_and_b32_e32 v43, 0xffff0000, v40
	v_pk_add_f32 v[38:39], v[38:39], v[42:43]
	v_lshlrev_b32_e32 v42, 16, v44
	v_and_b32_e32 v43, 0xffff0000, v44
	v_pk_add_f32 v[38:39], v[38:39], v[42:43]
	v_lshlrev_b32_e32 v42, 16, v48
	v_and_b32_e32 v43, 0xffff0000, v48
	v_pk_add_f32 v[38:39], v[38:39], v[42:43]
	v_lshlrev_b32_e32 v42, 16, v52
	v_and_b32_e32 v43, 0xffff0000, v52
	v_pk_add_f32 v[38:39], v[38:39], v[42:43]
	v_lshlrev_b32_e32 v42, 16, v56
	v_and_b32_e32 v43, 0xffff0000, v56
	v_pk_add_f32 v[38:39], v[38:39], v[42:43]
	v_lshlrev_b32_e32 v42, 16, v37
	v_pk_fma_f32 v[38:39], v[74:75], v[38:39], v[62:63] op_sel_hi:[0,1,1] neg_lo:[0,0,1] neg_hi:[0,0,1]
	v_cvt_pk_bf16_f32 v36, v38, v39
	v_pk_add_f32 v[38:39], v[64:65], v[72:73]
	v_and_b32_e32 v43, 0xffff0000, v37
	v_pk_add_f32 v[38:39], v[38:39], v[42:43]
	v_lshlrev_b32_e32 v40, 16, v41
	v_and_b32_e32 v41, 0xffff0000, v41
	v_pk_add_f32 v[38:39], v[38:39], v[40:41]
	v_lshlrev_b32_e32 v40, 16, v45
	v_and_b32_e32 v41, 0xffff0000, v45
	v_pk_add_f32 v[38:39], v[38:39], v[40:41]
	v_lshlrev_b32_e32 v40, 16, v49
	v_and_b32_e32 v41, 0xffff0000, v49
	v_pk_add_f32 v[38:39], v[38:39], v[40:41]
	v_lshlrev_b32_e32 v40, 16, v53
	v_and_b32_e32 v41, 0xffff0000, v53
	v_pk_add_f32 v[38:39], v[38:39], v[40:41]
	v_lshlrev_b32_e32 v40, 16, v57
	v_and_b32_e32 v41, 0xffff0000, v57
	v_pk_add_f32 v[38:39], v[38:39], v[40:41]
	v_add_u32_e32 v33, s72, v186
	v_pk_fma_f32 v[38:39], v[74:75], v[38:39], v[64:65] op_sel_hi:[0,1,1] neg_lo:[0,0,1] neg_hi:[0,0,1]
	v_cvt_pk_bf16_f32 v37, v38, v39
	ds_write_b128 v185, v[34:37] offset:21504
	ds_read_b128 v[34:37], v185 offset:12784
	ds_read_b128 v[38:41], v185 offset:12512
	v_and_b32_e32 v33, 0x7ff, v33
	v_min_u32_e32 v33, 7, v33
	v_add_u32_e32 v33, 1, v33
	s_waitcnt lgkmcnt(1)
	v_lshlrev_b32_e32 v58, 16, v34
	v_and_b32_e32 v59, 0xffff0000, v34
	s_waitcnt lgkmcnt(0)
	v_lshlrev_b32_e32 v66, 16, v38
	v_and_b32_e32 v67, 0xffff0000, v38
	v_lshlrev_b32_e32 v60, 16, v35
	v_and_b32_e32 v61, 0xffff0000, v35
	v_lshlrev_b32_e32 v62, 16, v36
	v_and_b32_e32 v63, 0xffff0000, v36
	v_lshlrev_b32_e32 v64, 16, v37
	v_and_b32_e32 v65, 0xffff0000, v37
	v_lshlrev_b32_e32 v68, 16, v39
	v_and_b32_e32 v69, 0xffff0000, v39
	v_lshlrev_b32_e32 v70, 16, v40
	v_and_b32_e32 v71, 0xffff0000, v40
	v_lshlrev_b32_e32 v72, 16, v41
	v_and_b32_e32 v73, 0xffff0000, v41
	ds_read_b128 v[34:37], v185 offset:12240
	ds_read_b128 v[38:41], v185 offset:11968
	ds_read_b128 v[42:45], v185 offset:11696
	ds_read_b128 v[46:49], v185 offset:11424
	ds_read_b128 v[50:53], v185 offset:11152
	ds_read_b128 v[54:57], v185 offset:10880
	v_pk_add_f32 v[66:67], v[58:59], v[66:67]
	s_waitcnt lgkmcnt(5)
; #define LAS __attribute__((address_space(3)))
; #define LBAR() do { asm volatile("s_waitcnt lgkmcnt(0)" ::: "memory"); __builtin_amdgcn_s_barrier(); asm volatile("" ::: "memory"); } while (0)
; __device__ __forceinline__ unsigned pk2(float lo, float hi) { return pg8::cvt_pk_bf16(lo, hi); }
; __device__ __forceinline__ f32x4 mfma16(bf16x8 a, bf16x8 b, f32x4 c) { return __builtin_amdgcn_mfma_f32_16x16x32_bf16(a, b, c, 0, 0, 0); }
; template <int WIN>
; __device__ __forceinline__ void pool_block_t(LAS unsigned char* lds, const Ptrs& P, int g, int tile0, int tstep, int tid) {
;     ...
;         for (int rep = 0; rep < 2; ++rep) {
;             const int row = vrow0 + 32 * rep; const int pos = (tile * 64 + row) & 2047; const int cnt = (pos + 1 < WIN) ? pos + 1 : WIN;
;             const v4u cur = *(const LAS v4u*)(Us + (row + 15) * S136 + vseg * 8); float a[8];
; #pragma unroll
;             for (int k = 0; k < 4; ++k) { a[2 * k] = bflo(cur[k]); a[2 * k + 1] = bfhi(cur[k]); }
; #pragma unroll
;             for (int tau = 1; tau < WIN; ++tau) { const v4u v = *(const LAS v4u*)(Us + (row + 15 - tau) * S136 + vseg * 8);
; #pragma unroll
;                 for (int k = 0; k < 4; ++k) { a[2 * k] += bflo(v[k]); a[2 * k + 1] += bfhi(v[k]); } }
;             const float inv = __builtin_amdgcn_rcpf((float)cnt); v4u o;
; #pragma unroll
;             for (int k = 0; k < 4; ++k) o[k] = pk2(a[2 * k] * inv - bflo(cur[k]), a[2 * k + 1] * inv - bfhi(cur[k]));
;             *(LAS v4u*)(Ps + row * S136 + vseg * 8) = o;
;         }
;         LBAR();
; #pragma unroll
;         for (int it = 0; it < 4; ++it) { f32x4 acc = (f32x4){0.f, 0.f, 0.f, 0.f};
; #pragma unroll
;             for (int ks = 0; ks < 4; ++ks) { const bf16x8 a = *(const LAS bf16x8*)(Ps + (16 * it + fr) * S136 + 32 * ks + 8 * fq); acc = mfma16(bw[ks], a, acc); }
;             v2u pw; pw.x = pk2(acc[0], acc[1]); pw.y = pk2(acc[2], acc[3]);
;             *(LAS v2u*)(Ys + (16 * it + fr) * S136 + 16 * w + 4 * fq) = pw; }
;         LBAR();
; #pragma unroll
;         for (int rep = 0; rep < 2; ++rep) { const int row = vrow0 + 32 * rep; const size_t t = (size_t)tile * 64 + row;
;             *(v4u*)(P.RS + t * 1024 + 512 + g * 128 + vseg * 8) = *(const LAS v4u*)(Ys + row * S136 + vseg * 8); }
	v_lshlrev_b32_e32 v76, 16, v34
	v_and_b32_e32 v77, 0xffff0000, v34
	v_pk_add_f32 v[66:67], v[66:67], v[76:77]
	s_waitcnt lgkmcnt(4)
	v_lshlrev_b32_e32 v76, 16, v38
	v_and_b32_e32 v77, 0xffff0000, v38
	v_cvt_f32_ubyte0_e32 v33, v33
	v_pk_add_f32 v[66:67], v[66:67], v[76:77]
	s_waitcnt lgkmcnt(3)
	v_lshlrev_b32_e32 v76, 16, v42
	v_and_b32_e32 v77, 0xffff0000, v42
	v_rcp_iflag_f32_e32 v74, v33
	v_pk_add_f32 v[66:67], v[66:67], v[76:77]
	s_waitcnt lgkmcnt(2)
	v_lshlrev_b32_e32 v76, 16, v46
	v_and_b32_e32 v77, 0xffff0000, v46
	v_pk_add_f32 v[66:67], v[66:67], v[76:77]
	s_waitcnt lgkmcnt(1)
	v_lshlrev_b32_e32 v76, 16, v50
	v_and_b32_e32 v77, 0xffff0000, v50
	v_pk_add_f32 v[66:67], v[66:67], v[76:77]
	s_waitcnt lgkmcnt(0)
	v_lshlrev_b32_e32 v76, 16, v54
	v_and_b32_e32 v77, 0xffff0000, v54
	v_pk_add_f32 v[66:67], v[66:67], v[76:77]
	v_lshlrev_b32_e32 v38, 16, v39
	v_pk_fma_f32 v[58:59], v[74:75], v[66:67], v[58:59] op_sel_hi:[0,1,1] neg_lo:[0,0,1] neg_hi:[0,0,1]
	v_cvt_pk_bf16_f32 v34, v58, v59
	v_pk_add_f32 v[58:59], v[60:61], v[68:69]
	v_lshlrev_b32_e32 v66, 16, v35
	v_and_b32_e32 v67, 0xffff0000, v35
	v_pk_add_f32 v[58:59], v[58:59], v[66:67]
	v_and_b32_e32 v39, 0xffff0000, v39
	v_pk_add_f32 v[38:39], v[58:59], v[38:39]
	v_lshlrev_b32_e32 v42, 16, v43
	v_and_b32_e32 v43, 0xffff0000, v43
	v_pk_add_f32 v[38:39], v[38:39], v[42:43]
	v_lshlrev_b32_e32 v42, 16, v47
	v_and_b32_e32 v43, 0xffff0000, v47
	v_pk_add_f32 v[38:39], v[38:39], v[42:43]
	v_lshlrev_b32_e32 v42, 16, v51
	v_and_b32_e32 v43, 0xffff0000, v51
	v_pk_add_f32 v[38:39], v[38:39], v[42:43]
	v_lshlrev_b32_e32 v42, 16, v55
	v_and_b32_e32 v43, 0xffff0000, v55
	v_pk_add_f32 v[38:39], v[38:39], v[42:43]
	v_lshlrev_b32_e32 v42, 16, v36
	v_pk_fma_f32 v[38:39], v[74:75], v[38:39], v[60:61] op_sel_hi:[0,1,1] neg_lo:[0,0,1] neg_hi:[0,0,1]
	v_cvt_pk_bf16_f32 v35, v38, v39
	v_pk_add_f32 v[38:39], v[62:63], v[70:71]
	v_and_b32_e32 v43, 0xffff0000, v36
	v_pk_add_f32 v[38:39], v[38:39], v[42:43]
	v_lshlrev_b32_e32 v42, 16, v40
	v_and_b32_e32 v43, 0xffff0000, v40
	v_pk_add_f32 v[38:39], v[38:39], v[42:43]
	v_lshlrev_b32_e32 v42, 16, v44
	v_and_b32_e32 v43, 0xffff0000, v44
	v_pk_add_f32 v[38:39], v[38:39], v[42:43]
	v_lshlrev_b32_e32 v42, 16, v48
	v_and_b32_e32 v43, 0xffff0000, v48
	v_pk_add_f32 v[38:39], v[38:39], v[42:43]
	v_lshlrev_b32_e32 v42, 16, v52
	v_and_b32_e32 v43, 0xffff0000, v52
	v_pk_add_f32 v[38:39], v[38:39], v[42:43]
	v_lshlrev_b32_e32 v42, 16, v56
	v_and_b32_e32 v43, 0xffff0000, v56
	v_pk_add_f32 v[38:39], v[38:39], v[42:43]
	v_lshlrev_b32_e32 v42, 16, v37
	v_pk_fma_f32 v[38:39], v[74:75], v[38:39], v[62:63] op_sel_hi:[0,1,1] neg_lo:[0,0,1] neg_hi:[0,0,1]
	v_cvt_pk_bf16_f32 v36, v38, v39
	v_pk_add_f32 v[38:39], v[64:65], v[72:73]
	v_and_b32_e32 v43, 0xffff0000, v37
	v_pk_add_f32 v[38:39], v[38:39], v[42:43]
	v_lshlrev_b32_e32 v40, 16, v41
	v_and_b32_e32 v41, 0xffff0000, v41
	v_pk_add_f32 v[38:39], v[38:39], v[40:41]
	v_lshlrev_b32_e32 v40, 16, v45
	v_and_b32_e32 v41, 0xffff0000, v45
	v_pk_add_f32 v[38:39], v[38:39], v[40:41]
	v_lshlrev_b32_e32 v40, 16, v49
	v_and_b32_e32 v41, 0xffff0000, v49
	v_pk_add_f32 v[38:39], v[38:39], v[40:41]
	v_lshlrev_b32_e32 v40, 16, v53
	v_and_b32_e32 v41, 0xffff0000, v53
	v_pk_add_f32 v[38:39], v[38:39], v[40:41]
	v_lshlrev_b32_e32 v40, 16, v57
	v_and_b32_e32 v41, 0xffff0000, v57
	v_pk_add_f32 v[38:39], v[38:39], v[40:41]
	v_add_u32_e32 v33, v184, v187
	v_pk_fma_f32 v[38:39], v[74:75], v[38:39], v[64:65] op_sel_hi:[0,1,1] neg_lo:[0,0,1] neg_hi:[0,0,1]
	v_cvt_pk_bf16_f32 v37, v38, v39
	ds_write_b128 v33, v[34:37] offset:21504
	s_waitcnt lgkmcnt(0)
	s_barrier
	ds_read_b128 v[224:227], v188 offset:21504
	ds_read_b128 v[228:231], v188 offset:21568
	ds_read_b128 v[232:235], v188 offset:21632
	ds_read_b128 v[236:239], v188 offset:21696
	ds_read_b128 v[240:243], v188 offset:25856
	ds_read_b128 v[244:247], v188 offset:25920
	ds_read_b128 v[252:255], v188 offset:25984
	ds_read_b128 v[38:41], v188 offset:26048
	s_waitcnt lgkmcnt(7)
	v_mfma_f32_16x16x32_bf16 v[34:37], v[0:3], v[224:227], 0
	s_mov_b32 s72, s71
	s_waitcnt lgkmcnt(6)
	v_mfma_f32_16x16x32_bf16 v[34:37], v[4:7], v[228:231], v[34:37]
	s_waitcnt lgkmcnt(5)
	v_mfma_f32_16x16x32_bf16 v[34:37], v[8:11], v[232:235], v[34:37]
	s_waitcnt lgkmcnt(4)
	v_mfma_f32_16x16x32_bf16 v[34:37], v[12:15], v[236:239], v[34:37]
	ds_read_b128 v[224:227], v188 offset:30208
	ds_read_b128 v[228:231], v188 offset:30272
	ds_read_b128 v[232:235], v188 offset:30336
	ds_read_b128 v[236:239], v188 offset:30400
	s_nop 7
	v_cvt_pk_bf16_f32 v34, v34, v35
	v_cvt_pk_bf16_f32 v35, v36, v37
	ds_write_b64 v32, v[34:35] offset:38912
	s_waitcnt lgkmcnt(8)
	v_mfma_f32_16x16x32_bf16 v[34:37], v[0:3], v[240:243], 0
	s_waitcnt lgkmcnt(7)
	v_mfma_f32_16x16x32_bf16 v[34:37], v[4:7], v[244:247], v[34:37]
	s_waitcnt lgkmcnt(6)
	v_mfma_f32_16x16x32_bf16 v[34:37], v[8:11], v[252:255], v[34:37]
	s_waitcnt lgkmcnt(5)
	v_mfma_f32_16x16x32_bf16 v[34:37], v[12:15], v[38:41], v[34:37]
	ds_read_b128 v[240:243], v188 offset:34560
	ds_read_b128 v[244:247], v188 offset:34624
	ds_read_b128 v[252:255], v188 offset:34688
	ds_read_b128 v[38:41], v188 offset:34752
	s_nop 7
	v_cvt_pk_bf16_f32 v34, v34, v35
	v_cvt_pk_bf16_f32 v35, v36, v37
	ds_write_b64 v32, v[34:35] offset:43264
	s_waitcnt lgkmcnt(9)
	v_mfma_f32_16x16x32_bf16 v[34:37], v[0:3], v[224:227], 0
	s_waitcnt lgkmcnt(8)
	v_mfma_f32_16x16x32_bf16 v[34:37], v[4:7], v[228:231], v[34:37]
	s_waitcnt lgkmcnt(7)
	v_mfma_f32_16x16x32_bf16 v[34:37], v[8:11], v[232:235], v[34:37]
	s_waitcnt lgkmcnt(6)
	v_mfma_f32_16x16x32_bf16 v[34:37], v[12:15], v[236:239], v[34:37]
	s_nop 7
	v_cvt_pk_bf16_f32 v34, v34, v35
	v_cvt_pk_bf16_f32 v35, v36, v37
	ds_write_b64 v32, v[34:35] offset:47616
	s_waitcnt lgkmcnt(5)
	v_mfma_f32_16x16x32_bf16 v[34:37], v[0:3], v[240:243], 0
	s_waitcnt lgkmcnt(4)
	v_mfma_f32_16x16x32_bf16 v[34:37], v[4:7], v[244:247], v[34:37]
	s_waitcnt lgkmcnt(3)
	v_mfma_f32_16x16x32_bf16 v[34:37], v[8:11], v[252:255], v[34:37]
	s_waitcnt lgkmcnt(2)
	v_mfma_f32_16x16x32_bf16 v[34:37], v[12:15], v[38:41], v[34:37]
	s_nop 7
	v_cvt_pk_bf16_f32 v34, v34, v35
	v_cvt_pk_bf16_f32 v35, v36, v37
	ds_write_b64 v32, v[34:35] offset:51968
	s_waitcnt lgkmcnt(0)
	s_barrier
	ds_read_b128 v[34:37], v185 offset:38912
	ds_read_b128 v[38:41], v33 offset:38912
	s_waitcnt lgkmcnt(1)
	global_store_dwordx4 v[28:29], v[34:37], off
	s_nop 1
	v_add_co_u32_e32 v34, vcc, 0x10000, v28
	s_nop 1
	v_addc_co_u32_e32 v35, vcc, 0, v29, vcc
	v_lshl_add_u64 v[28:29], v[28:29], 0, s[20:21]
	s_andn2_b64 vcc, exec, s[56:57]
	s_waitcnt lgkmcnt(0)
	global_store_dwordx4 v[34:35], v[38:41], off
	s_cbranch_vccz .LBB0_577
	s_waitcnt vmcnt(2)
	s_branch .Lpool1_top

; #define LAS __attribute__((address_space(3)))
; #define LBAR() do { asm volatile("s_waitcnt lgkmcnt(0)" ::: "memory"); __builtin_amdgcn_s_barrier(); asm volatile("" ::: "memory"); } while (0)
; __device__ __forceinline__ unsigned pk2(float lo, float hi) { return pg8::cvt_pk_bf16(lo, hi); }
; __device__ __forceinline__ f32x4 mfma16(bf16x8 a, bf16x8 b, f32x4 c) { return __builtin_amdgcn_mfma_f32_16x16x32_bf16(a, b, c, 0, 0, 0); }
; template <int WIN>
; __device__ __forceinline__ void pool_block_t(LAS unsigned char* lds, const Ptrs& P, int g, int tile0, int tstep, int tid) {
;     ...
;         for (int rep = 0; rep < 2; ++rep) {
;             const int row = vrow0 + 32 * rep; const int pos = (tile * 64 + row) & 2047; const int cnt = (pos + 1 < WIN) ? pos + 1 : WIN;
;             const v4u cur = *(const LAS v4u*)(Us + (row + 15) * S136 + vseg * 8); float a[8];
; #pragma unroll
;             for (int k = 0; k < 4; ++k) { a[2 * k] = bflo(cur[k]); a[2 * k + 1] = bfhi(cur[k]); }
; #pragma unroll
;             for (int tau = 1; tau < WIN; ++tau) { const v4u v = *(const LAS v4u*)(Us + (row + 15 - tau) * S136 + vseg * 8);
; #pragma unroll
;                 for (int k = 0; k < 4; ++k) { a[2 * k] += bflo(v[k]); a[2 * k + 1] += bfhi(v[k]); } }
;             const float inv = __builtin_amdgcn_rcpf((float)cnt); v4u o;
; #pragma unroll
;             for (int k = 0; k < 4; ++k) o[k] = pk2(a[2 * k] * inv - bflo(cur[k]), a[2 * k + 1] * inv - bfhi(cur[k]));
;             *(LAS v4u*)(Ps + row * S136 + vseg * 8) = o;
;         }
;         LBAR();
; #pragma unroll
;         for (int it = 0; it < 4; ++it) { f32x4 acc = (f32x4){0.f, 0.f, 0.f, 0.f};
; #pragma unroll
;             for (int ks = 0; ks < 4; ++ks) { const bf16x8 a = *(const LAS bf16x8*)(Ps + (16 * it + fr) * S136 + 32 * ks + 8 * fq); acc = mfma16(bw[ks], a, acc); }
;             v2u pw; pw.x = pk2(acc[0], acc[1]); pw.y = pk2(acc[2], acc[3]);
;             *(LAS v2u*)(Ys + (16 * it + fr) * S136 + 16 * w + 4 * fq) = pw; }
;         LBAR();
; #pragma unroll
;         for (int rep = 0; rep < 2; ++rep) { const int row = vrow0 + 32 * rep; const size_t t = (size_t)tile * 64 + row;
;             *(v4u*)(P.RS + t * 1024 + 512 + g * 128 + vseg * 8) = *(const LAS v4u*)(Ys + row * S136 + vseg * 8); }
.LBB0_590:
	s_and_b32 s58, s71, 0x7c0
	v_or_b32_e32 v33, s58, v80
	ds_read_b128 v[34:37], v194 offset:4080
	ds_read_b128 v[38:41], v194 offset:3808
	v_cmp_eq_u32_e32 vcc, 0, v33
	s_waitcnt lgkmcnt(1)
	v_lshlrev_b32_e32 v44, 16, v34
	v_cndmask_b32_e64 v33, 2, 1, vcc
	v_cvt_f32_ubyte0_e32 v33, v33
	v_rcp_iflag_f32_e32 v42, v33
	v_and_b32_e32 v45, 0xffff0000, v34
	s_waitcnt lgkmcnt(0)
	v_lshlrev_b32_e32 v46, 16, v38
	v_and_b32_e32 v47, 0xffff0000, v38
	v_pk_add_f32 v[46:47], v[44:45], v[46:47]
	v_lshlrev_b32_e32 v38, 16, v39
	v_pk_fma_f32 v[44:45], v[42:43], v[46:47], v[44:45] op_sel_hi:[0,1,1] neg_lo:[0,0,1] neg_hi:[0,0,1]
	v_cvt_pk_bf16_f32 v34, v44, v45
	v_lshlrev_b32_e32 v44, 16, v35
	v_and_b32_e32 v45, 0xffff0000, v35
	v_and_b32_e32 v39, 0xffff0000, v39
	v_pk_add_f32 v[38:39], v[44:45], v[38:39]
	v_add_u32_e32 v33, s71, v186
	v_pk_fma_f32 v[38:39], v[42:43], v[38:39], v[44:45] op_sel_hi:[0,1,1] neg_lo:[0,0,1] neg_hi:[0,0,1]
	v_cvt_pk_bf16_f32 v35, v38, v39
	v_lshlrev_b32_e32 v38, 16, v36
	v_and_b32_e32 v39, 0xffff0000, v36
	v_lshlrev_b32_e32 v44, 16, v40
	v_and_b32_e32 v45, 0xffff0000, v40
	v_pk_add_f32 v[44:45], v[38:39], v[44:45]
	v_lshlrev_b32_e32 v40, 16, v41
	v_pk_fma_f32 v[38:39], v[42:43], v[44:45], v[38:39] op_sel_hi:[0,1,1] neg_lo:[0,0,1] neg_hi:[0,0,1]
	v_cvt_pk_bf16_f32 v36, v38, v39
	v_lshlrev_b32_e32 v38, 16, v37
	v_and_b32_e32 v39, 0xffff0000, v37
	v_and_b32_e32 v41, 0xffff0000, v41
	v_pk_add_f32 v[40:41], v[38:39], v[40:41]
	v_and_b32_e32 v33, 0x7ff, v33
	v_pk_fma_f32 v[38:39], v[42:43], v[40:41], v[38:39] op_sel_hi:[0,1,1] neg_lo:[0,0,1] neg_hi:[0,0,1]
	v_cvt_pk_bf16_f32 v37, v38, v39
	ds_write_b128 v185, v[34:37] offset:21504
	ds_read_b128 v[34:37], v195 offset:4080
	ds_read_b128 v[38:41], v195 offset:3808
	v_cmp_eq_u32_e32 vcc, 0, v33
	s_mov_b32 s71, s70
	s_waitcnt lgkmcnt(1)
	v_lshlrev_b32_e32 v44, 16, v34
	v_cndmask_b32_e64 v33, 2, 1, vcc
	v_cvt_f32_ubyte0_e32 v33, v33
	v_rcp_iflag_f32_e32 v42, v33
	v_and_b32_e32 v45, 0xffff0000, v34
	s_waitcnt lgkmcnt(0)
	v_lshlrev_b32_e32 v46, 16, v38
	v_and_b32_e32 v47, 0xffff0000, v38
	v_pk_add_f32 v[46:47], v[44:45], v[46:47]
	v_lshlrev_b32_e32 v38, 16, v39
	v_pk_fma_f32 v[44:45], v[42:43], v[46:47], v[44:45] op_sel_hi:[0,1,1] neg_lo:[0,0,1] neg_hi:[0,0,1]
	v_cvt_pk_bf16_f32 v34, v44, v45
	v_lshlrev_b32_e32 v44, 16, v35
	v_and_b32_e32 v45, 0xffff0000, v35
	v_and_b32_e32 v39, 0xffff0000, v39
	v_pk_add_f32 v[38:39], v[44:45], v[38:39]
	v_add_u32_e32 v33, v184, v187
	v_pk_fma_f32 v[38:39], v[42:43], v[38:39], v[44:45] op_sel_hi:[0,1,1] neg_lo:[0,0,1] neg_hi:[0,0,1]
	v_cvt_pk_bf16_f32 v35, v38, v39
	v_lshlrev_b32_e32 v38, 16, v36
	v_and_b32_e32 v39, 0xffff0000, v36
	v_lshlrev_b32_e32 v44, 16, v40
	v_and_b32_e32 v45, 0xffff0000, v40
	v_pk_add_f32 v[44:45], v[38:39], v[44:45]
	v_lshlrev_b32_e32 v40, 16, v41
	v_pk_fma_f32 v[38:39], v[42:43], v[44:45], v[38:39] op_sel_hi:[0,1,1] neg_lo:[0,0,1] neg_hi:[0,0,1]
	v_cvt_pk_bf16_f32 v36, v38, v39
	v_lshlrev_b32_e32 v38, 16, v37
	v_and_b32_e32 v39, 0xffff0000, v37
	v_and_b32_e32 v41, 0xffff0000, v41
	v_pk_add_f32 v[40:41], v[38:39], v[40:41]
	s_nop 0
	v_pk_fma_f32 v[38:39], v[42:43], v[40:41], v[38:39] op_sel_hi:[0,1,1] neg_lo:[0,0,1] neg_hi:[0,0,1]
	v_cvt_pk_bf16_f32 v37, v38, v39
	ds_write_b128 v33, v[34:37] offset:21504
	s_waitcnt lgkmcnt(0)
	s_barrier
	ds_read_b128 v[224:227], v188 offset:21504
	ds_read_b128 v[228:231], v188 offset:21568
	ds_read_b128 v[232:235], v188 offset:21632
	ds_read_b128 v[236:239], v188 offset:21696
	ds_read_b128 v[240:243], v188 offset:25856
	ds_read_b128 v[244:247], v188 offset:25920
	ds_read_b128 v[252:255], v188 offset:25984
	ds_read_b128 v[38:41], v188 offset:26048
	s_waitcnt lgkmcnt(7)
	v_mfma_f32_16x16x32_bf16 v[34:37], v[0:3], v[224:227], 0
	s_waitcnt lgkmcnt(6)
	v_mfma_f32_16x16x32_bf16 v[34:37], v[4:7], v[228:231], v[34:37]
	s_waitcnt lgkmcnt(5)
	v_mfma_f32_16x16x32_bf16 v[34:37], v[8:11], v[232:235], v[34:37]
	s_waitcnt lgkmcnt(4)
	v_mfma_f32_16x16x32_bf16 v[34:37], v[12:15], v[236:239], v[34:37]
	ds_read_b128 v[224:227], v188 offset:30208
	ds_read_b128 v[228:231], v188 offset:30272
	ds_read_b128 v[232:235], v188 offset:30336
	ds_read_b128 v[236:239], v188 offset:30400
	s_nop 7
	v_cvt_pk_bf16_f32 v34, v34, v35
	v_cvt_pk_bf16_f32 v35, v36, v37
	ds_write_b64 v32, v[34:35] offset:38912
	s_waitcnt lgkmcnt(8)
	v_mfma_f32_16x16x32_bf16 v[34:37], v[0:3], v[240:243], 0
	s_waitcnt lgkmcnt(7)
	v_mfma_f32_16x16x32_bf16 v[34:37], v[4:7], v[244:247], v[34:37]
	s_waitcnt lgkmcnt(6)
	v_mfma_f32_16x16x32_bf16 v[34:37], v[8:11], v[252:255], v[34:37]
	s_waitcnt lgkmcnt(5)
	v_mfma_f32_16x16x32_bf16 v[34:37], v[12:15], v[38:41], v[34:37]
	ds_read_b128 v[240:243], v188 offset:34560
	ds_read_b128 v[244:247], v188 offset:34624
	ds_read_b128 v[252:255], v188 offset:34688
	ds_read_b128 v[38:41], v188 offset:34752
	s_nop 7
	v_cvt_pk_bf16_f32 v34, v34, v35
	v_cvt_pk_bf16_f32 v35, v36, v37
	ds_write_b64 v32, v[34:35] offset:43264
	s_waitcnt lgkmcnt(9)
	v_mfma_f32_16x16x32_bf16 v[34:37], v[0:3], v[224:227], 0
	s_waitcnt lgkmcnt(8)
	v_mfma_f32_16x16x32_bf16 v[34:37], v[4:7], v[228:231], v[34:37]
	s_waitcnt lgkmcnt(7)
	v_mfma_f32_16x16x32_bf16 v[34:37], v[8:11], v[232:235], v[34:37]
	s_waitcnt lgkmcnt(6)
	v_mfma_f32_16x16x32_bf16 v[34:37], v[12:15], v[236:239], v[34:37]
	s_nop 7
	v_cvt_pk_bf16_f32 v34, v34, v35
	v_cvt_pk_bf16_f32 v35, v36, v37
	ds_write_b64 v32, v[34:35] offset:47616
	s_waitcnt lgkmcnt(5)
	v_mfma_f32_16x16x32_bf16 v[34:37], v[0:3], v[240:243], 0
	s_waitcnt lgkmcnt(4)
	v_mfma_f32_16x16x32_bf16 v[34:37], v[4:7], v[244:247], v[34:37]
	s_waitcnt lgkmcnt(3)
	v_mfma_f32_16x16x32_bf16 v[34:37], v[8:11], v[252:255], v[34:37]
	s_waitcnt lgkmcnt(2)
	v_mfma_f32_16x16x32_bf16 v[34:37], v[12:15], v[38:41], v[34:37]
	s_nop 7
	v_cvt_pk_bf16_f32 v34, v34, v35
	v_cvt_pk_bf16_f32 v35, v36, v37
	ds_write_b64 v32, v[34:35] offset:51968
	s_waitcnt lgkmcnt(0)
	s_barrier
	ds_read_b128 v[34:37], v185 offset:38912
	ds_read_b128 v[38:41], v33 offset:38912
	s_waitcnt lgkmcnt(1)
	global_store_dwordx4 v[28:29], v[34:37], off
	s_nop 1
	v_add_co_u32_e32 v34, vcc, 0x10000, v28
	s_nop 1
	v_addc_co_u32_e32 v35, vcc, 0, v29, vcc
	v_lshl_add_u64 v[28:29], v[28:29], 0, s[20:21]
	s_andn2_b64 vcc, exec, s[56:57]
	s_waitcnt lgkmcnt(0)
	global_store_dwordx4 v[34:35], v[38:41], off
	s_cbranch_vccz .LBB0_604
	s_waitcnt vmcnt(2)
	s_branch .Lpool2_top

; #define LAS __attribute__((address_space(3)))
; #define LBAR() do { asm volatile("s_waitcnt lgkmcnt(0)" ::: "memory"); __builtin_amdgcn_s_barrier(); asm volatile("" ::: "memory"); } while (0)
; __device__ __forceinline__ unsigned pk2(float lo, float hi) { return pg8::cvt_pk_bf16(lo, hi); }
; template <int WIN>
; __device__ __forceinline__ void pool_block_t(LAS unsigned char* lds, const Ptrs& P, int g, int tile0, int tstep, int tid) {
;     ...
;         for (int rep = 0; rep < 2; ++rep) {
;             const int row = vrow0 + 32 * rep; const int pos = (tile * 64 + row) & 2047; const int cnt = (pos + 1 < WIN) ? pos + 1 : WIN;
;             const v4u cur = *(const LAS v4u*)(Us + (row + 15) * S136 + vseg * 8); float a[8];
; #pragma unroll
;             for (int k = 0; k < 4; ++k) { a[2 * k] = bflo(cur[k]); a[2 * k + 1] = bfhi(cur[k]); }
; #pragma unroll
;             for (int tau = 1; tau < WIN; ++tau) { const v4u v = *(const LAS v4u*)(Us + (row + 15 - tau) * S136 + vseg * 8);
; #pragma unroll
;                 for (int k = 0; k < 4; ++k) { a[2 * k] += bflo(v[k]); a[2 * k + 1] += bfhi(v[k]); } }
;             const float inv = __builtin_amdgcn_rcpf((float)cnt); v4u o;
; #pragma unroll
;             for (int k = 0; k < 4; ++k) o[k] = pk2(a[2 * k] * inv - bflo(cur[k]), a[2 * k + 1] * inv - bfhi(cur[k]));
;             *(LAS v4u*)(Ps + row * S136 + vseg * 8) = o;
;         }
;         LBAR();
.LBB0_615:
	s_and_b32 s20, s63, 0x7c0
	v_or_b32_e32 v33, s20, v80
	v_min_u32_e32 v33, 3, v33
	ds_read_b128 v[34:37], v185 offset:4080
	ds_read_b128 v[38:41], v185 offset:3808
	ds_read_b128 v[42:45], v185 offset:3536
	ds_read_b128 v[46:49], v185 offset:3264
	v_add_u32_e32 v33, 1, v33
	v_cvt_f32_ubyte0_e32 v33, v33
	v_rcp_iflag_f32_e32 v50, v33
	s_waitcnt lgkmcnt(3)
	v_lshlrev_b32_e32 v52, 16, v34
	v_and_b32_e32 v53, 0xffff0000, v34
	s_waitcnt lgkmcnt(2)
	v_lshlrev_b32_e32 v54, 16, v38
	v_and_b32_e32 v55, 0xffff0000, v38
	v_pk_add_f32 v[54:55], v[52:53], v[54:55]
	s_waitcnt lgkmcnt(1)
	v_lshlrev_b32_e32 v56, 16, v42
	v_and_b32_e32 v57, 0xffff0000, v42
	v_pk_add_f32 v[54:55], v[54:55], v[56:57]
	s_waitcnt lgkmcnt(0)
	v_lshlrev_b32_e32 v56, 16, v46
	v_and_b32_e32 v57, 0xffff0000, v46
	v_pk_add_f32 v[54:55], v[54:55], v[56:57]
	v_lshlrev_b32_e32 v38, 16, v39
	v_pk_fma_f32 v[52:53], v[50:51], v[54:55], v[52:53] op_sel_hi:[0,1,1] neg_lo:[0,0,1] neg_hi:[0,0,1]
	v_cvt_pk_bf16_f32 v34, v52, v53
	v_lshlrev_b32_e32 v52, 16, v35
	v_and_b32_e32 v53, 0xffff0000, v35
	v_and_b32_e32 v39, 0xffff0000, v39
	v_pk_add_f32 v[38:39], v[52:53], v[38:39]
	v_lshlrev_b32_e32 v42, 16, v43
	v_and_b32_e32 v43, 0xffff0000, v43
	v_pk_add_f32 v[38:39], v[38:39], v[42:43]
	v_lshlrev_b32_e32 v42, 16, v47
	v_and_b32_e32 v43, 0xffff0000, v47
	v_pk_add_f32 v[38:39], v[38:39], v[42:43]
	v_lshlrev_b32_e32 v42, 16, v40
	v_pk_fma_f32 v[38:39], v[50:51], v[38:39], v[52:53] op_sel_hi:[0,1,1] neg_lo:[0,0,1] neg_hi:[0,0,1]
	v_cvt_pk_bf16_f32 v35, v38, v39
	v_lshlrev_b32_e32 v38, 16, v36
	v_and_b32_e32 v39, 0xffff0000, v36
	v_and_b32_e32 v43, 0xffff0000, v40
	v_pk_add_f32 v[42:43], v[38:39], v[42:43]
	v_lshlrev_b32_e32 v46, 16, v44
	v_and_b32_e32 v47, 0xffff0000, v44
	v_pk_add_f32 v[42:43], v[42:43], v[46:47]
	v_lshlrev_b32_e32 v46, 16, v48
	v_and_b32_e32 v47, 0xffff0000, v48
	v_pk_add_f32 v[42:43], v[42:43], v[46:47]
	v_lshlrev_b32_e32 v40, 16, v41
	v_pk_fma_f32 v[38:39], v[50:51], v[42:43], v[38:39] op_sel_hi:[0,1,1] neg_lo:[0,0,1] neg_hi:[0,0,1]
	v_cvt_pk_bf16_f32 v36, v38, v39
	v_lshlrev_b32_e32 v38, 16, v37
	v_and_b32_e32 v39, 0xffff0000, v37
	v_and_b32_e32 v41, 0xffff0000, v41
	v_pk_add_f32 v[40:41], v[38:39], v[40:41]
	v_lshlrev_b32_e32 v42, 16, v45
	v_and_b32_e32 v43, 0xffff0000, v45
	v_pk_add_f32 v[40:41], v[40:41], v[42:43]
	v_lshlrev_b32_e32 v42, 16, v49
	v_and_b32_e32 v43, 0xffff0000, v49
	v_pk_add_f32 v[40:41], v[40:41], v[42:43]
	v_add_u32_e32 v33, s63, v186
	v_pk_fma_f32 v[38:39], v[50:51], v[40:41], v[38:39] op_sel_hi:[0,1,1] neg_lo:[0,0,1] neg_hi:[0,0,1]
	v_cvt_pk_bf16_f32 v37, v38, v39
	ds_write_b128 v185, v[34:37] offset:21504
	v_and_b32_e32 v33, 0x7ff, v33
	v_min_u32_e32 v33, 3, v33
	ds_read_b128 v[34:37], v185 offset:12784
	ds_read_b128 v[38:41], v185 offset:12512
	ds_read_b128 v[42:45], v185 offset:12240
	ds_read_b128 v[46:49], v185 offset:11968
	v_add_u32_e32 v33, 1, v33
	v_cvt_f32_ubyte0_e32 v33, v33
	v_rcp_iflag_f32_e32 v50, v33
	s_waitcnt lgkmcnt(3)
	v_lshlrev_b32_e32 v52, 16, v34
	v_and_b32_e32 v53, 0xffff0000, v34
	s_waitcnt lgkmcnt(2)
	v_lshlrev_b32_e32 v54, 16, v38
	v_and_b32_e32 v55, 0xffff0000, v38
	v_pk_add_f32 v[54:55], v[52:53], v[54:55]
	s_waitcnt lgkmcnt(1)
	v_lshlrev_b32_e32 v56, 16, v42
	v_and_b32_e32 v57, 0xffff0000, v42
	v_pk_add_f32 v[54:55], v[54:55], v[56:57]
	s_waitcnt lgkmcnt(0)
	v_lshlrev_b32_e32 v56, 16, v46
	v_and_b32_e32 v57, 0xffff0000, v46
	v_pk_add_f32 v[54:55], v[54:55], v[56:57]
	v_lshlrev_b32_e32 v38, 16, v39
	v_pk_fma_f32 v[52:53], v[50:51], v[54:55], v[52:53] op_sel_hi:[0,1,1] neg_lo:[0,0,1] neg_hi:[0,0,1]
	v_cvt_pk_bf16_f32 v34, v52, v53
	v_lshlrev_b32_e32 v52, 16, v35
	v_and_b32_e32 v53, 0xffff0000, v35
	v_and_b32_e32 v39, 0xffff0000, v39
	v_pk_add_f32 v[38:39], v[52:53], v[38:39]
	v_lshlrev_b32_e32 v42, 16, v43
	v_and_b32_e32 v43, 0xffff0000, v43
	v_pk_add_f32 v[38:39], v[38:39], v[42:43]
	v_lshlrev_b32_e32 v42, 16, v47
	v_and_b32_e32 v43, 0xffff0000, v47
	v_pk_add_f32 v[38:39], v[38:39], v[42:43]
	v_lshlrev_b32_e32 v42, 16, v40
	v_pk_fma_f32 v[38:39], v[50:51], v[38:39], v[52:53] op_sel_hi:[0,1,1] neg_lo:[0,0,1] neg_hi:[0,0,1]
	v_cvt_pk_bf16_f32 v35, v38, v39
	v_lshlrev_b32_e32 v38, 16, v36
	v_and_b32_e32 v39, 0xffff0000, v36
	v_and_b32_e32 v43, 0xffff0000, v40
	v_pk_add_f32 v[42:43], v[38:39], v[42:43]
	v_lshlrev_b32_e32 v46, 16, v44
	v_and_b32_e32 v47, 0xffff0000, v44
	v_pk_add_f32 v[42:43], v[42:43], v[46:47]
	v_lshlrev_b32_e32 v46, 16, v48
	v_and_b32_e32 v47, 0xffff0000, v48
	v_pk_add_f32 v[42:43], v[42:43], v[46:47]
	v_lshlrev_b32_e32 v40, 16, v41
	v_pk_fma_f32 v[38:39], v[50:51], v[42:43], v[38:39] op_sel_hi:[0,1,1] neg_lo:[0,0,1] neg_hi:[0,0,1]
	v_cvt_pk_bf16_f32 v36, v38, v39
	v_lshlrev_b32_e32 v38, 16, v37
	v_and_b32_e32 v39, 0xffff0000, v37
	v_and_b32_e32 v41, 0xffff0000, v41
	v_pk_add_f32 v[40:41], v[38:39], v[40:41]
	v_lshlrev_b32_e32 v42, 16, v45
	v_and_b32_e32 v43, 0xffff0000, v45
	v_pk_add_f32 v[40:41], v[40:41], v[42:43]
	v_lshlrev_b32_e32 v42, 16, v49
	v_and_b32_e32 v43, 0xffff0000, v49
	v_pk_add_f32 v[40:41], v[40:41], v[42:43]
	v_add_u32_e32 v33, v184, v187
	v_pk_fma_f32 v[38:39], v[50:51], v[40:41], v[38:39] op_sel_hi:[0,1,1] neg_lo:[0,0,1] neg_hi:[0,0,1]
	v_cvt_pk_bf16_f32 v37, v38, v39
	ds_write_b128 v33, v[34:37] offset:21504
	s_waitcnt lgkmcnt(0)
	s_barrier
; #define LAS __attribute__((address_space(3)))
; #define LBAR() do { asm volatile("s_waitcnt lgkmcnt(0)" ::: "memory"); __builtin_amdgcn_s_barrier(); asm volatile("" ::: "memory"); } while (0)
; __device__ __forceinline__ unsigned pk2(float lo, float hi) { return pg8::cvt_pk_bf16(lo, hi); }
; __device__ __forceinline__ f32x4 mfma16(bf16x8 a, bf16x8 b, f32x4 c) { return __builtin_amdgcn_mfma_f32_16x16x32_bf16(a, b, c, 0, 0, 0); }
; template <int WIN>
; __device__ __forceinline__ void pool_block_t(LAS unsigned char* lds, const Ptrs& P, int g, int tile0, int tstep, int tid) {
;     ...
; #pragma unroll
;         for (int it = 0; it < 4; ++it) { f32x4 acc = (f32x4){0.f, 0.f, 0.f, 0.f};
; #pragma unroll
;             for (int ks = 0; ks < 4; ++ks) { const bf16x8 a = *(const LAS bf16x8*)(Ps + (16 * it + fr) * S136 + 32 * ks + 8 * fq); acc = mfma16(bw[ks], a, acc); }
;             v2u pw; pw.x = pk2(acc[0], acc[1]); pw.y = pk2(acc[2], acc[3]);
;             *(LAS v2u*)(Ys + (16 * it + fr) * S136 + 16 * w + 4 * fq) = pw; }
;         LBAR();
; #pragma unroll
;         for (int rep = 0; rep < 2; ++rep) { const int row = vrow0 + 32 * rep; const size_t t = (size_t)tile * 64 + row;
;             *(v4u*)(P.RS + t * 1024 + 512 + g * 128 + vseg * 8) = *(const LAS v4u*)(Ys + row * S136 + vseg * 8); }
	ds_read_b128 v[224:227], v188 offset:21504
	ds_read_b128 v[228:231], v188 offset:21568
	ds_read_b128 v[232:235], v188 offset:21632
	ds_read_b128 v[236:239], v188 offset:21696
	ds_read_b128 v[240:243], v188 offset:25856
	ds_read_b128 v[244:247], v188 offset:25920
	ds_read_b128 v[252:255], v188 offset:25984
	ds_read_b128 v[38:41], v188 offset:26048
	s_waitcnt lgkmcnt(7)
	v_mfma_f32_16x16x32_bf16 v[34:37], v[0:3], v[224:227], 0
	s_mov_b32 s63, s62
	s_waitcnt lgkmcnt(6)
	v_mfma_f32_16x16x32_bf16 v[34:37], v[4:7], v[228:231], v[34:37]
	s_waitcnt lgkmcnt(5)
	v_mfma_f32_16x16x32_bf16 v[34:37], v[8:11], v[232:235], v[34:37]
	s_waitcnt lgkmcnt(4)
	v_mfma_f32_16x16x32_bf16 v[34:37], v[12:15], v[236:239], v[34:37]
	ds_read_b128 v[224:227], v188 offset:30208
	ds_read_b128 v[228:231], v188 offset:30272
	ds_read_b128 v[232:235], v188 offset:30336
	ds_read_b128 v[236:239], v188 offset:30400
	s_nop 7
	v_cvt_pk_bf16_f32 v34, v34, v35
	v_cvt_pk_bf16_f32 v35, v36, v37
	ds_write_b64 v32, v[34:35] offset:38912
	s_waitcnt lgkmcnt(8)
	v_mfma_f32_16x16x32_bf16 v[34:37], v[0:3], v[240:243], 0
	s_waitcnt lgkmcnt(7)
	v_mfma_f32_16x16x32_bf16 v[34:37], v[4:7], v[244:247], v[34:37]
	s_waitcnt lgkmcnt(6)
	v_mfma_f32_16x16x32_bf16 v[34:37], v[8:11], v[252:255], v[34:37]
	s_waitcnt lgkmcnt(5)
	v_mfma_f32_16x16x32_bf16 v[34:37], v[12:15], v[38:41], v[34:37]
	ds_read_b128 v[240:243], v188 offset:34560
	ds_read_b128 v[244:247], v188 offset:34624
	ds_read_b128 v[252:255], v188 offset:34688
	ds_read_b128 v[38:41], v188 offset:34752
	s_nop 7
	v_cvt_pk_bf16_f32 v34, v34, v35
	v_cvt_pk_bf16_f32 v35, v36, v37
	ds_write_b64 v32, v[34:35] offset:43264
	s_waitcnt lgkmcnt(9)
	v_mfma_f32_16x16x32_bf16 v[34:37], v[0:3], v[224:227], 0
	s_waitcnt lgkmcnt(8)
	v_mfma_f32_16x16x32_bf16 v[34:37], v[4:7], v[228:231], v[34:37]
	s_waitcnt lgkmcnt(7)
	v_mfma_f32_16x16x32_bf16 v[34:37], v[8:11], v[232:235], v[34:37]
	s_waitcnt lgkmcnt(6)
	v_mfma_f32_16x16x32_bf16 v[34:37], v[12:15], v[236:239], v[34:37]
	s_nop 7
	v_cvt_pk_bf16_f32 v34, v34, v35
	v_cvt_pk_bf16_f32 v35, v36, v37
	ds_write_b64 v32, v[34:35] offset:47616
	s_waitcnt lgkmcnt(5)
	v_mfma_f32_16x16x32_bf16 v[34:37], v[0:3], v[240:243], 0
	s_waitcnt lgkmcnt(4)
	v_mfma_f32_16x16x32_bf16 v[34:37], v[4:7], v[244:247], v[34:37]
	s_waitcnt lgkmcnt(3)
	v_mfma_f32_16x16x32_bf16 v[34:37], v[8:11], v[252:255], v[34:37]
	s_waitcnt lgkmcnt(2)
	v_mfma_f32_16x16x32_bf16 v[34:37], v[12:15], v[38:41], v[34:37]
	s_nop 7
	v_cvt_pk_bf16_f32 v34, v34, v35
	v_cvt_pk_bf16_f32 v35, v36, v37
	ds_write_b64 v32, v[34:35] offset:51968
	s_waitcnt lgkmcnt(0)
	s_barrier
	ds_read_b128 v[34:37], v185 offset:38912
	ds_read_b128 v[38:41], v33 offset:38912
	s_waitcnt lgkmcnt(1)
	global_store_dwordx4 v[28:29], v[34:37], off
	s_nop 1
	v_add_co_u32_e32 v34, vcc, 0x10000, v28
	s_nop 1
	v_addc_co_u32_e32 v35, vcc, 0, v29, vcc
	v_lshl_add_u64 v[28:29], v[28:29], 0, s[16:17]
	s_andn2_b64 vcc, exec, s[18:19]
	s_waitcnt lgkmcnt(0)
	global_store_dwordx4 v[34:35], v[38:41], off
	s_cbranch_vccz .LBB0_629
	s_waitcnt vmcnt(2)
	s_branch .Lpool3_top
